# phase E load balance: the 320 S5 GEMM units go 2 each to workgroups 0..159, none to 160..255 (which keep 7 gate units); slowest workgroup now 2 S5 + 6 gate units instead of 1 + 7
# speedup vs baseline: 1.0199x; 1.0028x over previous
;     __device__ __forceinline__ bool next(int i, Unit& u) const {
;         const int L = i * G + c; if (L >= total) return false;
;         u.batch = L / nwg; std_map(L - u.batch * nwg, nM, nN, u.pm, u.pn); if (skipctx) u.pm += (u.pm >> 4) + 1; return true;
; __global__ __launch_bounds__(512, 2) void mega(Args a_) {
;     ...
;             pg8::gemm_phase<false, true>(lds, pg8::StdProb(WSP(OFF_A2), WSP(OFF_BTY), 768, 768, 768, (size_t)NCR * 768, (size_t)512 * 768, 5, 2, 32, G, c), EpiYP{WSP(OFF_R2 + SZ_ACT)});
.LBB0_680:
	s_andn2_b64 vcc, exec, s[0:1]
	s_cbranch_vccnz .LBB0_803
	v_readlane_b32 s4, v237, 2
	v_readlane_b32 s5, v237, 3
	s_mov_b64 s[0:1], s[4:5]
	s_mov_b32 s6, s46
	s_load_dwordx2 s[2:3], s[4:5], 0xf0
	s_mov_b32 s22, s84
	v_mov_b32_e32 v0, v216
	s_waitcnt lgkmcnt(0)
	s_mov_b32 s46, s2
	s_mov_b32 s100, s46
	s_cmpk_lg_i32 s46, 0x100
	s_cbranch_scc1 .Le_keep
	s_movk_i32 s46, 0xa0
	s_cmpk_lt_i32 s22, 0xa0
	s_cselect_b32 s22, s22, 0x140
.Le_keep:
	s_cmpk_lt_i32 s22, 0x140
	s_cselect_b64 s[4:5], -1, 0
	s_cmpk_gt_i32 s22, 0x13f
	v_readfirstlane_b32 s8, v0
	s_cbranch_scc1 .LBB0_683
	s_mul_hi_i32 s2, s22, 0x66666667
	s_lshr_b32 s3, s2, 31
	s_ashr_i32 s2, s2, 2
	s_add_i32 s49, s2, s3
	s_mul_i32 s2, s49, -10
	s_add_i32 s2, s2, s22
	s_ashr_i32 s3, s2, 31
	s_lshr_b32 s3, s3, 29
	s_add_i32 s3, s2, s3
	s_ashr_i32 s9, s3, 3
	s_and_b32 s3, s3, -8
	s_sub_i32 s2, s2, s3
	s_lshl_b32 s3, s2, 1
	s_add_i32 s14, s2, 2
	s_cmp_lt_i32 s2, 2
	s_cselect_b32 s2, s3, s14
	s_add_i32 s2, s2, s9
	s_ashr_i32 s3, s2, 31
	s_lshr_b32 s3, s3, 28
	s_add_i32 s3, s2, s3
	s_ashr_i32 s9, s3, 4
	s_lshl_b32 s9, s9, 3
	s_sub_i32 s14, 5, s9
	s_min_i32 s14, s14, 8
	s_abs_i32 s15, s14
	v_cvt_f32_u32_e32 v2, s15
	s_sub_i32 s17, 0, s15
	s_and_b32 s3, s3, -16
	s_sub_i32 s3, s2, s3
	v_rcp_iflag_f32_e32 v2, v2
	s_abs_i32 s2, s3
	s_xor_b32 s16, s3, s14
	s_ashr_i32 s16, s16, 31
	v_mul_f32_e32 v2, 0x4f7ffffe, v2
	v_cvt_u32_f32_e32 v2, v2
	s_nop 0
	v_readfirstlane_b32 s18, v2
	s_mul_i32 s17, s17, s18
	s_mul_hi_u32 s17, s18, s17
	s_add_i32 s18, s18, s17
	s_mul_hi_u32 s17, s2, s18
	s_mul_i32 s18, s17, s15
	s_sub_i32 s2, s2, s18
	s_add_i32 s18, s17, 1
	s_sub_i32 s19, s2, s15
	s_cmp_ge_u32 s2, s15
	s_cselect_b32 s17, s18, s17
	s_cselect_b32 s2, s19, s2
	s_add_i32 s18, s17, 1
	s_cmp_ge_u32 s2, s15
	s_cselect_b32 s2, s18, s17
	s_xor_b32 s2, s2, s16
	s_sub_i32 s2, s2, s16
	s_mul_i32 s14, s2, s14
	s_sub_i32 s3, s3, s14
	s_add_i32 s3, s3, s9

; #define LAS __attribute__((address_space(3)))
;     __device__ __forceinline__ long bhalf(const Unit&) const { return (long)HALF * ldb * 2; }
; template <bool HM = false, bool PERM = false, bool CP = false, class Prob, class Epi>
; __device__ __forceinline__ void gemm_phase(LAS unsigned char* lds, const Prob& S, const Epi& E) {
;     int tid = threadIdx.x; asm volatile("" : "+v"(tid));
;     const int wid = __builtin_amdgcn_readfirstlane(tid >> 6), lane = tid & 63, wr = wid >> 2, wc = wid & 3, fr = lane & 15, fq = lane >> 4;
;     unsigned voffA[2], voffB[2];
; #pragma unroll
;     for (int i = 0; i < 2; ++i) { int R, C; stage_rc(tid * 16 + i * 8192, R, C); const int Rb = PERM ? ((R & ~31) + perm32(R & 31)) : R; voffA[i] = (unsigned)(R * S.lda + C) * 2u; voffB[i] = (unsigned)(Rb * S.ldb + C) * 2u; }
;     const size_t kstepA = S.kstepA(), kstepB = S.kstepB();
;     const size_t hstepA = HM ? 0 : (size_t)HALF * S.lda * 2; const long hstepB0 = (long)HALF * S.ldb * 2;
;     const unsigned ldsw = (unsigned)wid * 1024u;
;     const int aoff = lds_byte(wr * 64 + fr, fq * 8), boff = lds_byte(wc * 32 + fr, fq * 8);
;     ...
;     Unit cur, nxt; int ui = 0;
;     if (!S.next(0, cur)) return;
;     f32x4 acc[2][2][4][2];
; #pragma unroll
;     for (int a = 0; a < 2; ++a)
; #pragma unroll
;         for (int b = 0; b < 2; ++b)
; #pragma unroll
;             for (int m = 0; m < 4; ++m)
; #pragma unroll
;                 for (int n = 0; n < 2; ++n) acc[a][b][m][n] = (f32x4){0.f, 0.f, 0.f, 0.f};
;     bf16x8 At[4][2], B0[2][2], B1[2][2];
;     const char* cA = S.abase(cur);
;     const char* cB = S.bbase(cur);
;     long chB = CP ? S.bhalf(cur) : hstepB0; bool fullu = CP ? S.full(cur) : true;
;     ...
;     PG8_STAGE(PG8_SB(0, 0), cB, voffB); PG8_STAGE(PG8_SB(0, 1), cB + chB, voffB); PG8_STAGE(PG8_SA(0, 0), cA, voffA); PG8_STAGE(PG8_SA(0, 1), cA + hstepA, voffA);
;     if (wr == 1) PG8_BAR;
;     PG8_WAIT_V(2); PG8_BAR;
;     PG8_STAGE(PG8_SB(1, 0), cB + kstepB, voffB); PG8_STAGE(PG8_SA(1, 0), cA + kstepA, voffA); PG8_STAGE(PG8_SB(1, 1), cB + chB + kstepB, voffB);
; __global__ __launch_bounds__(512, 2) void mega(Args a_) {
;     ...
;             { pg8::StdProb P(WSP(OFF_HN), WSP(OFF_WA + WA_WIN) + (size_t)3584 * DM, DM, DM, DM, 0, 0, l == DEPTH - 1 ? 128 : 136, 12, 1, G, G - 1 - c);     P.skipctx = l == DEPTH - 1;
;               pg8::gemm_phase<false, true>(lds, P, EpiGatesP{WSP(OFF_R1)}); }
.LBB0_719:
	s_mov_b32 s46, s100
	s_mov_b32 s22, s84
	s_cmp_eq_u32 s6, 3
	s_cselect_b64 s[4:5], -1, 0
	s_and_b64 s[0:1], s[4:5], exec
	s_movk_i32 s0, 0x88
	s_cselect_b32 s2, 0x80, s0
	s_not_b32 s0, s22
	s_add_i32 s3, s46, s0
	s_mul_i32 s18, s2, 12
	v_mov_b32_e32 v16, v216
	s_cmp_ge_i32 s3, s18
	v_readfirstlane_b32 s22, v16
	s_cbranch_scc1 .LBB0_735
	v_lshlrev_b32_e32 v0, 4, v16
	v_add_u32_e32 v2, 0x2000, v0
	v_ashrrev_i32_e32 v3, 31, v2
	v_lshrrev_b32_e32 v3, 22, v3
	v_add_u32_e32 v3, v2, v3
	v_ashrrev_i32_e32 v10, 10, v3
	v_mul_i32_i24_e32 v3, 0x400, v10
	v_sub_u32_e32 v2, v2, v3
	v_lshrrev_b32_e32 v3, 4, v2
	v_bitop3_b32 v2, v3, v2, 32 bitop3:0x6c
	v_ashrrev_i32_e32 v3, 31, v2
	v_lshrrev_b32_e32 v3, 26, v3
	v_add_u32_e32 v3, v2, v3
	v_lshlrev_b32_e32 v4, 3, v10
	v_ashrrev_i32_e32 v11, 6, v3
	v_and_b32_e32 v4, -16, v4
	v_add_u32_e32 v4, v11, v4
	v_and_b32_e32 v5, 3, v11
	s_mov_b32 s0, 0x1fffe0
	v_lshrrev_b32_e32 v6, 2, v4
	v_lshlrev_b32_e32 v7, 1, v4
	v_and_b32_e32 v3, 0xc0, v3
	v_and_or_b32 v5, v4, s0, v5
	v_and_b32_e32 v6, 4, v6
	v_and_b32_e32 v7, 24, v7
	v_sub_u32_e32 v2, v2, v3
	v_or3_b32 v5, v5, v6, v7
	v_lshlrev_b32_e32 v6, 5, v10
	v_ashrrev_i16_sdwa v2, v220, sext(v2) dst_sel:DWORD dst_unused:UNUSED_PAD src0_sel:DWORD src1_sel:BYTE_0
	v_and_b32_e32 v6, 32, v6
	v_bfe_i32 v12, v2, 0, 16
	v_add_lshl_u32 v2, v6, v12, 1
	v_lshl_add_u32 v130, v5, 11, v2
	v_lshl_add_u32 v132, v4, 11, v2
	v_bfe_i32 v2, v16, 27, 1
	v_lshrrev_b32_e32 v2, 22, v2
	v_add_u32_e32 v2, v0, v2
	v_and_b32_e32 v2, 0xfffffc00, v2
	v_sub_u32_e32 v0, v0, v2
	v_lshrrev_b32_e32 v2, 4, v0
	v_ashrrev_i32_e32 v3, 31, v16
	v_bitop3_b32 v0, v2, v0, 32 bitop3:0x6c
	v_lshrrev_b32_e32 v3, 26, v3
	v_ashrrev_i32_e32 v2, 31, v0
	v_add_u32_e32 v3, v16, v3
	v_lshrrev_b32_e32 v2, 26, v2
	v_ashrrev_i32_e32 v14, 6, v3
	v_add_u32_e32 v2, v0, v2
	v_lshlrev_b32_e32 v3, 3, v14
	v_ashrrev_i32_e32 v13, 6, v2
	v_and_b32_e32 v3, -16, v3
	v_add_u32_e32 v3, v13, v3
	v_and_b32_e32 v4, 3, v13
	v_lshrrev_b32_e32 v5, 2, v3
	v_lshlrev_b32_e32 v6, 1, v3
	v_and_or_b32 v4, v3, s0, v4
	v_and_b32_e32 v5, 4, v5
	v_and_b32_e32 v6, 24, v6
	v_or3_b32 v4, v4, v5, v6
	v_cvt_f32_u32_e32 v6, s18
	v_and_b32_e32 v2, 0xc0, v2
	v_sub_u32_e32 v0, v0, v2
	s_waitcnt lgkmcnt(0)
	s_add_u32 s19, s14, 0x33f8000
	v_rcp_iflag_f32_e32 v2, v6
	s_addc_u32 s31, s15, 0
	s_add_u32 s33, s14, 0x17f8000
	s_addc_u32 s47, s15, 0
	v_mul_f32_e32 v2, 0x4f7ffffe, v2
	v_cvt_u32_f32_e32 v2, v2
	s_sub_i32 s6, 0, s18
	s_abs_i32 s1, s3
	s_ashr_i32 s23, s22, 6
	v_readfirstlane_b32 s49, v2
	s_mul_i32 s6, s6, s49
	s_mul_hi_u32 s6, s49, s6
	s_add_i32 s49, s49, s6
	s_mul_hi_u32 s6, s1, s49
	s_mul_i32 s6, s6, s18
	s_sub_i32 s1, s1, s6
	s_ashr_i32 s34, s22, 8
	s_lshl_b32 s48, s23, 10
	s_ashr_i32 s0, s3, 31
	s_sub_i32 s6, s1, s18
	s_cmp_ge_u32 s1, s18
	s_cselect_b32 s1, s6, s1
	s_sub_i32 s6, s1, s18
	s_cmp_ge_u32 s1, s18
	s_cselect_b32 s1, s6, s1
	s_xor_b32 s1, s1, s0
	s_sub_i32 s0, s1, s0
	s_sext_i32_i16 s1, s0
	s_bfe_u32 s1, s1, 0x3001c
	s_add_i32 s1, s0, s1
	s_and_b32 s6, s1, 0xfff8
	s_sub_i32 s0, s0, s6
	s_lshr_b32 s52, s18, 3
	s_bfe_u32 s6, s0, 0x1000f
	s_or_b32 s6, s52, s6
	s_sext_i32_i16 s1, s1
	s_mul_i32 s0, s6, s0
	s_ashr_i32 s1, s1, 3
	s_add_i32 s0, s0, s1
	s_sext_i32_i16 s1, s0
	s_mulk_i32 s1, 0x2aab
	s_lshr_b32 s6, s1, 31
	s_ashr_i32 s1, s1, 20
	s_add_i32 s1, s1, s6
	s_lshl_b32 s8, s1, 3
	s_sub_i32 s6, s2, s8
	s_min_i32 s9, s6, 8
	s_sext_i32_i8 s6, s9
	v_cvt_f32_i32_e32 v2, s6
	v_lshlrev_b32_e32 v5, 5, v14
	v_ashrrev_i16_sdwa v0, v220, sext(v0) dst_sel:DWORD dst_unused:UNUSED_PAD src0_sel:DWORD src1_sel:BYTE_0
	s_mulk_i32 s1, 0x60
	v_and_b32_e32 v5, 32, v5
	v_bfe_i32 v15, v0, 0, 16
	s_sub_i32 s0, s0, s1
	v_add_lshl_u32 v5, v5, v15, 1
	s_sext_i32_i16 s16, s0
	v_lshl_add_u32 v0, v4, 11, v5
	v_lshl_add_u32 v134, v3, 11, v5
	v_cvt_f32_i32_e32 v3, s16
	v_rcp_iflag_f32_e32 v4, v2
	s_xor_b32 s0, s16, s6
	s_ashr_i32 s0, s0, 30
	s_or_b32 s6, s0, 1
	v_mul_f32_e32 v4, v3, v4
	v_trunc_f32_e32 v4, v4
	v_fma_f32 v3, -v4, v2, v3
	v_cvt_i32_f32_e32 v4, v4
	v_cmp_ge_f32_e64 s[0:1], |v3|, |v2|
	s_and_b64 s[0:1], s[0:1], exec
	s_cselect_b32 s0, s6, 0
	v_readfirstlane_b32 s1, v4
	s_add_i32 s6, s1, s0
	s_mul_i32 s0, s6, s9
	s_sub_i32 s0, s16, s0
	s_sext_i32_i8 s0, s0
	s_add_i32 s8, s8, s0
	s_ashr_i32 s0, s8, 4
	s_add_i32 s0, s8, s0
	s_add_i32 s9, s0, 1
	s_and_b64 s[0:1], s[4:5], exec
	s_cselect_b32 s8, s9, s8
	s_bfe_i64 s[0:1], s[6:7], 0x80000
	s_ashr_i32 s9, s8, 31
	s_lshl_b64 s[0:1], s[0:1], 19
	s_add_u32 s24, s33, s0
	s_addc_u32 s25, s47, s1
	s_add_i32 s53, s48, 0
	s_add_i32 m0, s53, 0x10000
	v_mov_b32_e32 v131, v1
	global_load_lds_dwordx4 v0, s[24:25]
	s_add_i32 m0, s53, 0x12000
	s_add_u32 s0, s24, 0x40000
	global_load_lds_dwordx4 v130, s[24:25]
	s_addc_u32 s1, s25, 0
	s_add_i32 m0, s53, 0x14000
	v_mov_b32_e32 v135, v1
	global_load_lds_dwordx4 v0, s[0:1]
	s_add_i32 m0, s53, 0x16000
	v_mov_b32_e32 v133, v1
	global_load_lds_dwordx4 v130, s[0:1]
	s_lshl_b64 s[0:1], s[8:9], 19
	s_add_u32 s0, s19, s0
	s_addc_u32 s1, s31, s1
	s_add_i32 s9, s53, 0x2000
	s_mov_b32 m0, s53
	s_add_u32 s16, s0, 0x40000
	global_load_lds_dwordx4 v134, s[0:1]
	s_mov_b32 m0, s9
	s_addc_u32 s17, s1, 0
	s_add_i32 s54, s53, 0x4000
	global_load_lds_dwordx4 v132, s[0:1]
	s_mov_b32 m0, s54
	s_add_i32 s55, s53, 0x6000
	global_load_lds_dwordx4 v134, s[16:17]
	s_mov_b32 m0, s55
	s_cmp_eq_u32 s34, 1
	global_load_lds_dwordx4 v132, s[16:17]
	v_lshl_add_u64 v[8:9], s[24:25], 0, v[0:1]
	v_lshl_add_u64 v[6:7], s[24:25], 0, v[130:131]
	v_lshl_add_u64 v[2:3], s[0:1], 0, v[134:135]
	s_cselect_b64 s[16:17], -1, 0
	s_cmp_lg_u32 s34, 1
	v_lshl_add_u64 v[4:5], s[0:1], 0, v[132:133]
	s_cbranch_scc1 .LBB0_722
	s_barrier
